# attention main loop hand-rescheduled (V/K LDS prefetch, in-place exps, max chain under PV MFMAs) + half-tile stagger of waves 4-7 with two barriers per tile; numerics unchanged
# speedup vs baseline: 1.0086x; 1.0086x over previous
; #define WAIT_BAR(N) asm volatile("s_waitcnt vmcnt(" #N ") lgkmcnt(0)\n\ts_barrier" ::: "memory")
; #define DMA_K(t, so) do { const char* b_ = (const char*)Kh + (size_t)(t) * (KVBLK * LDK * 2); const unsigned d_ = (unsigned)__builtin_amdgcn_readfirstlane(kdst + (so)); glds16(kof[0], b_, d_); glds16(kof[1], b_, d_ + 8192u); } while (0)
; #define DMA_V(t, so) do { const char* b_ = (const char*)Vh + (size_t)(t) * (KVBLK * LDK * 2); const unsigned d_ = (unsigned)__builtin_amdgcn_readfirstlane(vdst + (so)); glds16(vof[0], b_, d_); glds16(vof[1], b_, d_ + 8192u); } while (0)
; #define WAIT_BAR(N) asm volatile("s_waitcnt vmcnt(" #N ") lgkmcnt(0)\n\ts_barrier" ::: "memory")
; #define DMA_K(t, so) do { const char* b_ = (const char*)K8t + (size_t)(t) * (KVBLK * 256); glds16(kof, b_, (unsigned)__builtin_amdgcn_readfirstlane(kdst + (so))); } while (0)
; #define DMA_V(t, so) do { const char* b_ = (const char*)V8t + (size_t)(t) * 8192; glds16(vof, b_, (unsigned)__builtin_amdgcn_readfirstlane(vdst + (so))); } while (0)
; template <bool FIRST> __device__ __forceinline__ void partialSM8(f32x16& p0, f32x16& p1, float& m_ref, f32x16& negm, float& alpha) {
;     ...
;   const float delta = pmax - POFF8;
;   alpha = 1.f;
;   if (FIRST || !__builtin_expect(__all(delta <= THRL8), 1)) {
;     const float dl = FIRST ? delta : fmaxf(delta, 0.f);
;     m_ref += dl;
;     for (int r = 0; r < 16; ++r) { p0[r] -= dl; p1[r] -= dl; }
;     const float nm = POFF8 - m_ref;
;     for (int r = 0; r < 16; ++r) negm[r] = nm;
;     if (!FIRST) alpha = __builtin_amdgcn_exp2f(-dl);
;   }
;   for (int r = 0; r < 16; ++r) p0[r] = __builtin_amdgcn_exp2f(p0[r]);
; __device__ __forceinline__ void attn_fp8_body(const unsigned char* __restrict__ Q8w, const unsigned char* __restrict__ K8t, const unsigned char* __restrict__ V8t,
;                                               bf16_t* __restrict__ Ob, int seq, char* lds, const int tid) {
;     ...
;   f32x16 pA0, pA1, pB0, pB1; float alA, alB; v8i pa; const int NT = seq / KVBLK;
;   DMA_K(0, 0); DMA_V(0, 0); DMA_K(1, SLOT8);
;   WAIT_BAR(0);
;   DMA_K(2, 2 * SLOT8); DMA_V(1, SLOT8);
;   qkt8(pA0, pA1, KP8(0), qr, negm, r32, hi); partialSM8<true>(pA0, pA1, m_ref, negm, alA);
;   WAIT_BAR(2);
;   int s0 = 0, s1 = SLOT8, s2 = 2 * SLOT8;
;     ...
;   for (int j = 1; j + 1 < NT; j += 2) {
.LBB0_61:
	v_sub_f32_e32 v18, v18, v201
	v_sub_f32_e32 v19, v19, v201
	v_sub_f32_e32 v20, v20, v201
	v_sub_f32_e32 v21, v21, v201
	v_sub_f32_e32 v22, v22, v201
	v_sub_f32_e32 v23, v23, v201
	v_sub_f32_e32 v24, v24, v201
	v_sub_f32_e32 v25, v25, v201
	v_sub_f32_e32 v26, v26, v201
	v_sub_f32_e32 v27, v27, v201
	v_sub_f32_e32 v28, v28, v201
	v_sub_f32_e32 v29, v29, v201
	v_sub_f32_e32 v30, v30, v201
	v_sub_f32_e32 v31, v31, v201
	v_sub_f32_e32 v32, v32, v201
	v_sub_f32_e32 v33, v33, v201
	s_and_b32 s10, s10, 0x3fffffc0
	v_exp_f32_e32 v235, v18
	v_exp_f32_e32 v236, v19
	v_exp_f32_e32 v237, v20
	v_exp_f32_e32 v238, v21
	v_exp_f32_e32 v207, v22
	v_exp_f32_e32 v209, v23
	v_exp_f32_e32 v211, v24
	v_exp_f32_e32 v213, v25
	v_exp_f32_e32 v167, v26
	v_exp_f32_e32 v168, v27
	v_exp_f32_e32 v169, v28
	v_exp_f32_e32 v205, v29
	v_exp_f32_e32 v165, v30
	v_exp_f32_e32 v166, v31
	v_exp_f32_e32 v163, v32
	v_exp_f32_e32 v164, v33
	s_lshl_b32 s10, s10, 2
	s_add_i32 s23, s10, 0
	s_add_i32 s23, s23, 0x10000
	v_sub_f32_e32 v129, v17, v201
	v_sub_f32_e32 v128, v16, v201
	v_sub_f32_e32 v127, v15, v201
	v_sub_f32_e32 v126, v14, v201
	v_sub_f32_e32 v125, v13, v201
	v_sub_f32_e32 v124, v12, v201
	v_sub_f32_e32 v123, v11, v201
	v_sub_f32_e32 v122, v10, v201
	v_sub_f32_e32 v121, v9, v201
	v_sub_f32_e32 v120, v8, v201
	v_sub_f32_e32 v119, v7, v201
	v_sub_f32_e32 v118, v6, v201
	v_sub_f32_e32 v117, v5, v201
	v_sub_f32_e32 v116, v4, v201
	v_sub_f32_e32 v115, v3, v201
	s_andn2_b64 vcc, exec, s[8:9]
	v_sub_f32_e32 v114, v2, v201
	s_cbranch_vccnz .LBB0_77
	s_add_u32 s6, s6, 0x4000
	s_addc_u32 s7, s7, 0
	s_add_u32 s8, s4, 0xc000
	v_mov_b32_e32 v2, 0
	s_mov_b32 s39, 2
	v_lshl_add_u32 v203, v193, 2, s23
	s_addc_u32 s9, s5, 0
	s_movk_i32 s34, 0x4000
	s_movk_i32 s35, 0x2000
	s_mov_b32 s10, 0
	v_mov_b32_e32 v3, v2
	v_mov_b32_e32 v4, v2
	v_mov_b32_e32 v5, v2
	v_mov_b32_e32 v6, v2
	v_mov_b32_e32 v7, v2
	v_mov_b32_e32 v8, v2
	v_mov_b32_e32 v9, v2
	v_mov_b32_e32 v10, v2
	v_mov_b32_e32 v11, v2
	v_mov_b32_e32 v12, v2
	v_mov_b32_e32 v13, v2
	v_mov_b32_e32 v14, v2
	v_mov_b32_e32 v15, v2
	v_mov_b32_e32 v16, v2
	v_mov_b32_e32 v17, v2
	v_mov_b32_e32 v50, v2
	v_mov_b32_e32 v51, v2
	v_mov_b32_e32 v52, v2
	v_mov_b32_e32 v53, v2
	v_mov_b32_e32 v54, v2
	v_mov_b32_e32 v55, v2
	v_mov_b32_e32 v56, v2
	v_mov_b32_e32 v57, v2
	v_mov_b32_e32 v58, v2
	v_mov_b32_e32 v59, v2
	v_mov_b32_e32 v60, v2
	v_mov_b32_e32 v61, v2
	v_mov_b32_e32 v62, v2
	v_mov_b32_e32 v63, v2
	v_mov_b32_e32 v64, v2
	v_mov_b32_e32 v65, v2
	v_mov_b32_e32 v34, v2
	v_mov_b32_e32 v35, v2
	v_mov_b32_e32 v36, v2
	v_mov_b32_e32 v37, v2
	v_mov_b32_e32 v38, v2
	v_mov_b32_e32 v39, v2
	v_mov_b32_e32 v40, v2
	v_mov_b32_e32 v41, v2
	v_mov_b32_e32 v42, v2
	v_mov_b32_e32 v43, v2
	v_mov_b32_e32 v44, v2
	v_mov_b32_e32 v45, v2
	v_mov_b32_e32 v46, v2
	v_mov_b32_e32 v47, v2
	v_mov_b32_e32 v48, v2
	v_mov_b32_e32 v49, v2
	v_mov_b32_e32 v18, v2
	v_mov_b32_e32 v19, v2
	v_mov_b32_e32 v20, v2
	v_mov_b32_e32 v21, v2
	v_mov_b32_e32 v22, v2
	v_mov_b32_e32 v23, v2
	v_mov_b32_e32 v24, v2
	v_mov_b32_e32 v25, v2
	v_mov_b32_e32 v26, v2
	v_mov_b32_e32 v27, v2
	v_mov_b32_e32 v28, v2
	v_mov_b32_e32 v29, v2
	v_mov_b32_e32 v30, v2
	v_mov_b32_e32 v31, v2
	v_mov_b32_e32 v32, v2
	v_mov_b32_e32 v33, v2
	v_mov_b32_e32 v66, v2
	v_mov_b32_e32 v67, v2
	v_mov_b32_e32 v68, v2
	v_mov_b32_e32 v69, v2
	v_mov_b32_e32 v70, v2
	v_mov_b32_e32 v71, v2
	v_mov_b32_e32 v72, v2
	v_mov_b32_e32 v73, v2
	v_mov_b32_e32 v74, v2
	v_mov_b32_e32 v75, v2
	v_mov_b32_e32 v76, v2
	v_mov_b32_e32 v77, v2
	v_mov_b32_e32 v78, v2
	v_mov_b32_e32 v79, v2
	v_mov_b32_e32 v80, v2
	v_mov_b32_e32 v81, v2
	v_mov_b32_e32 v99, v98
	v_mov_b32_e32 v100, v98
	v_mov_b32_e32 v101, v98
	v_mov_b32_e32 v102, v98
	v_mov_b32_e32 v103, v98
	v_mov_b32_e32 v104, v98
	v_mov_b32_e32 v105, v98
	v_mov_b32_e32 v106, v98
	v_mov_b32_e32 v107, v98
	v_mov_b32_e32 v108, v98
	v_mov_b32_e32 v109, v98
	v_mov_b32_e32 v110, v98
	v_mov_b32_e32 v111, v98
	v_mov_b32_e32 v112, v98
	v_mov_b32_e32 v113, v98
	v_readlane_b32 s26, v253, 6
	s_nop 3
	s_cmp_lt_u32 s26, 4
	s_cbranch_scc1 .Lattn_h1_entry
	s_barrier
	s_branch .Lattn_h1_entry
.LBB0_63:
	v_exp_f32_e32 v235, v130
	v_exp_f32_e32 v236, v131
	v_exp_f32_e32 v237, v132
	v_exp_f32_e32 v238, v133
	v_exp_f32_e32 v207, v134
	v_exp_f32_e32 v209, v135
	v_exp_f32_e32 v211, v136
	v_exp_f32_e32 v213, v137
	v_exp_f32_e32 v167, v138
	v_exp_f32_e32 v168, v139
	v_exp_f32_e32 v169, v140
	v_exp_f32_e32 v205, v141
	v_exp_f32_e32 v165, v142
	v_exp_f32_e32 v166, v143
	v_exp_f32_e32 v163, v144
	v_exp_f32_e32 v164, v145
; __device__ __forceinline__ v8i cat8(v4i a, v4i b) { return (v8i){a[0], a[1], a[2], a[3], b[0], b[1], b[2], b[3]}; }
; __device__ __forceinline__ void finishSM8(f32x16& p0, f32x16& p1, v8i& pa) {
;   for (int r = 0; r < 16; ++r) p1[r] = __builtin_amdgcn_exp2f(p1[r]);
; #pragma unroll
;   for (int w = 0; w < 4; ++w) { int x = 0; x = __builtin_amdgcn_cvt_pk_fp8_f32(p0[4 * w], p0[4 * w + 1], x, false); x = __builtin_amdgcn_cvt_pk_fp8_f32(p0[4 * w + 2], p0[4 * w + 3], x, true); pa[w] = x; }
; #pragma unroll
;   for (int w = 0; w < 4; ++w) { int x = 0; x = __builtin_amdgcn_cvt_pk_fp8_f32(p1[4 * w], p1[4 * w + 1], x, false); x = __builtin_amdgcn_cvt_pk_fp8_f32(p1[4 * w + 2], p1[4 * w + 3], x, true); pa[4 + w] = x; }
; }
; __device__ __forceinline__ void qkt8(f32x16& p0, f32x16& p1, const char* Ks, const v8i* qr, const f32x16& negm, int r32, int hi) {
; #pragma unroll
;   for (int c = 0; c < 2; ++c) { const int b0 = 64 * c + 32 * hi;
;     const v8i a0 = cat8(*reinterpret_cast<const v4i*>(Ks + KSW8(r32, b0)), *reinterpret_cast<const v4i*>(Ks + KSW8(r32, b0 + 16)));
;     const v8i a1 = cat8(*reinterpret_cast<const v4i*>(Ks + KSW8(32 + r32, b0)), *reinterpret_cast<const v4i*>(Ks + KSW8(32 + r32, b0 + 16)));
;     if (c == 0) { p0 = __builtin_amdgcn_mfma_scale_f32_32x32x64_f8f6f4(a0, qr[c], negm, 0, 0, 0, 0, 0, 0); p1 = __builtin_amdgcn_mfma_scale_f32_32x32x64_f8f6f4(a1, qr[c], negm, 0, 0, 0, 0, 0, 0); }
;     else { p0 = __builtin_amdgcn_mfma_scale_f32_32x32x64_f8f6f4(a0, qr[c], p0, 0, 0, 0, 0, 0, 0); p1 = __builtin_amdgcn_mfma_scale_f32_32x32x64_f8f6f4(a1, qr[c], p1, 0, 0, 0, 0, 0, 0); } }
; }
; __device__ __forceinline__ void pv8(f32x16* o, const char* Vs, v8i pa, int r32, int hi) {
; #pragma unroll
;   for (int d0 = 0; d0 < 4; ++d0) { const int col = 32 * d0 + r32;
;     const v8i b = cat8(*reinterpret_cast<const v4i*>(Vs + VSW8(col, 32 * hi)), *reinterpret_cast<const v4i*>(Vs + VSW8(col, 32 * hi + 16)));
;     o[d0] = __builtin_amdgcn_mfma_scale_f32_32x32x64_f8f6f4(pa, b, o[d0], 0, 0, 0, 0, 0, 0); }
;   const int one4 = 0x38383838;
;   const v8i ones = (v8i){one4, one4, one4, one4, one4, one4, one4, one4};
;   o[4] = __builtin_amdgcn_mfma_scale_f32_32x32x64_f8f6f4(pa, ones, o[4], 0, 0, 0, 0, 0, 0);
; }
.Lattn_h1_entry:
	s_mov_b32 s49, s35
	s_mov_b32 s35, s10
	s_add_i32 s10, s10, s36
	s_add_i32 s50, s49, 0
	v_add_u32_e32 v90, s50, v219
	ds_read_b128 v[82:85], v90 offset:4096
	v_add_u32_e32 v94, s50, v220
	ds_read_b128 v[86:89], v94 offset:4096
	ds_read_b128 v[90:93], v90
	ds_read_b128 v[94:97], v94
	s_mov_b32 s11, m0
	s_mov_b32 m0, s10
	s_nop 0
	global_load_lds_dwordx4 v199, s[8:9]
	s_mov_b32 m0, s11
	v_exp_f32_e32 v114, v114
	v_exp_f32_e32 v115, v115
	v_exp_f32_e32 v116, v116
	v_exp_f32_e32 v117, v117
	v_exp_f32_e32 v118, v118
	v_exp_f32_e32 v119, v119
	s_waitcnt lgkmcnt(0)
	v_mfma_f32_32x32x64_f8f6f4 v[130:145], v[90:97], v[178:185], v[98:113]
	v_add_u32_e32 v90, s50, v221
	v_add_u32_e32 v94, s50, v222
	v_exp_f32_e32 v120, v120
	v_exp_f32_e32 v121, v121
	v_exp_f32_e32 v122, v122
	v_mfma_f32_32x32x64_f8f6f4 v[146:161], v[82:89], v[178:185], v[98:113]
	ds_read_b128 v[82:85], v90 offset:4096
	ds_read_b128 v[86:89], v94 offset:4096
	ds_read_b128 v[90:93], v90
	ds_read_b128 v[94:97], v94
	v_exp_f32_e32 v123, v123
	v_exp_f32_e32 v124, v124
	v_exp_f32_e32 v125, v125
	v_exp_f32_e32 v126, v126
	s_waitcnt lgkmcnt(0)
	v_mfma_f32_32x32x64_f8f6f4 v[130:145], v[90:97], v[170:177], v[130:145]
	v_exp_f32_e32 v127, v127
	v_exp_f32_e32 v128, v128
	v_exp_f32_e32 v129, v129
	v_mfma_f32_32x32x64_f8f6f4 v[146:161], v[82:89], v[170:177], v[146:161]
	s_waitcnt vmcnt(2) lgkmcnt(0)
	s_barrier
	s_add_i32 s26, s34, s38
	s_mov_b32 s11, m0
	s_mov_b32 m0, s26
	s_nop 0
	global_load_lds_dwordx4 v1, s[6:7]
	s_mov_b32 m0, s11
	s_add_i32 s10, s35, 0
	v_add_u32_e32 v90, s10, v223
	v_add_u32_e32 v94, s10, v224
	ds_read_b128 v[90:93], v90 offset:24576
	ds_read_b128 v[94:97], v94 offset:24576
	v_add_u32_e32 v82, s10, v223
	v_add_u32_e32 v86, s10, v224
	ds_read_b128 v[82:85], v82 offset:26624
	ds_read_b128 v[86:89], v86 offset:26624
	v_cvt_pk_fp8_f32 v119, v118, v119
	v_cvt_pk_fp8_f32 v118, v114, v115
	v_cvt_pk_fp8_f32 v119, v120, v121 op_sel:[0,0,1]
	v_cvt_pk_fp8_f32 v118, v116, v117 op_sel:[0,0,1]
	v_cvt_pk_fp8_f32 v120, v122, v123
	v_cvt_pk_fp8_f32 v121, v126, v127
	v_cvt_pk_fp8_f32 v120, v124, v125 op_sel:[0,0,1]
	v_cvt_pk_fp8_f32 v121, v128, v129 op_sel:[0,0,1]
	v_cvt_pk_fp8_f32 v114, v235, v236
	v_cvt_pk_fp8_f32 v115, v207, v209
	v_cvt_pk_fp8_f32 v116, v167, v168
	v_cvt_pk_fp8_f32 v117, v165, v166
	v_cvt_pk_fp8_f32 v114, v237, v238 op_sel:[0,0,1]
	v_cvt_pk_fp8_f32 v115, v211, v213 op_sel:[0,0,1]
	v_cvt_pk_fp8_f32 v116, v169, v205 op_sel:[0,0,1]
	v_cvt_pk_fp8_f32 v117, v163, v164 op_sel:[0,0,1]
	v_add_u32_e32 v124, s10, v223
	v_add_u32_e32 v125, s10, v224
	v_mov_b32_e32 v163, v162
	v_mov_b32_e32 v164, v162
	v_mov_b32_e32 v165, v162
	v_mov_b32_e32 v166, v162
	v_mov_b32_e32 v167, v162
	v_mov_b32_e32 v168, v162
	v_mov_b32_e32 v169, v162
	s_waitcnt lgkmcnt(2)
	v_mfma_f32_32x32x64_f8f6f4 v[2:17], v[114:121], v[90:97], v[2:17]
	ds_read_b128 v[90:93], v124 offset:28672
	ds_read_b128 v[94:97], v125 offset:28672
	v_max3_f32 v122, v130, v131, v132
	v_max3_f32 v123, v133, v134, v135
	v_max3_f32 v122, v122, v136, v137
	v_max3_f32 v123, v123, v138, v139
	v_max3_f32 v122, v122, v140, v141
	s_waitcnt lgkmcnt(2)
	v_mfma_f32_32x32x64_f8f6f4 v[50:65], v[114:121], v[82:89], v[50:65]
	ds_read_b128 v[82:85], v124 offset:30720
	ds_read_b128 v[86:89], v125 offset:30720
	v_max3_f32 v123, v123, v142, v143
	v_max3_f32 v122, v122, v144, v145
	v_max3_f32 v123, v123, v146, v147
	v_max3_f32 v122, v122, v148, v149
	v_max3_f32 v123, v123, v150, v151
	s_waitcnt lgkmcnt(2)
	v_mfma_f32_32x32x64_f8f6f4 v[34:49], v[114:121], v[90:97], v[34:49]
	v_max3_f32 v122, v122, v152, v153
	v_max3_f32 v123, v123, v154, v155
	v_max3_f32 v122, v122, v156, v157
	v_max3_f32 v123, v123, v158, v159
	v_max3_f32 v122, v122, v160, v161
	s_waitcnt lgkmcnt(0)
	v_mfma_f32_32x32x64_f8f6f4 v[18:33], v[114:121], v[82:89], v[18:33]
	v_mfma_f32_32x32x64_f8f6f4 v[66:81], v[114:121], v[162:169], v[66:81]
	v_max_f32_e32 v82, v122, v123
	v_mov_b32_e32 v83, v82
	s_nop 1
	v_permlane32_swap_b32_e32 v82, v83
	v_max_f32_e32 v83, v83, v83
	v_max_f32_e32 v82, v82, v82
	v_max_f32_e32 v82, v82, v83
	v_add_f32_e32 v82, -4.0, v82
	v_cmp_ge_f32_e32 vcc, s82, v82
	s_cmp_eq_u64 vcc, exec
	s_cbranch_scc0 .LBB0_75
	v_mov_b64_e32 v[82:83], v[98:99]
	v_mov_b32_e32 v114, 1.0
	v_mov_b64_e32 v[84:85], v[100:101]
	v_mov_b64_e32 v[86:87], v[102:103]
	v_mov_b64_e32 v[88:89], v[104:105]
	v_mov_b64_e32 v[90:91], v[106:107]
	v_mov_b64_e32 v[92:93], v[108:109]
	v_mov_b64_e32 v[94:95], v[110:111]
	v_mov_b64_e32 v[96:97], v[112:113]
	v_cmp_gt_f32_e32 vcc, 1.0, v114
	s_cbranch_vccz .LBB0_68

; __device__ __forceinline__ v8i cat8(v4i a, v4i b) { return (v8i){a[0], a[1], a[2], a[3], b[0], b[1], b[2], b[3]}; }
; __device__ __forceinline__ void finishSM8(f32x16& p0, f32x16& p1, v8i& pa) {
;   for (int r = 0; r < 16; ++r) p1[r] = __builtin_amdgcn_exp2f(p1[r]);
; #pragma unroll
;   for (int w = 0; w < 4; ++w) { int x = 0; x = __builtin_amdgcn_cvt_pk_fp8_f32(p0[4 * w], p0[4 * w + 1], x, false); x = __builtin_amdgcn_cvt_pk_fp8_f32(p0[4 * w + 2], p0[4 * w + 3], x, true); pa[w] = x; }
; #pragma unroll
;   for (int w = 0; w < 4; ++w) { int x = 0; x = __builtin_amdgcn_cvt_pk_fp8_f32(p1[4 * w], p1[4 * w + 1], x, false); x = __builtin_amdgcn_cvt_pk_fp8_f32(p1[4 * w + 2], p1[4 * w + 3], x, true); pa[4 + w] = x; }
; }
; __device__ __forceinline__ void qkt8(f32x16& p0, f32x16& p1, const char* Ks, const v8i* qr, const f32x16& negm, int r32, int hi) {
; #pragma unroll
;   for (int c = 0; c < 2; ++c) { const int b0 = 64 * c + 32 * hi;
;     const v8i a0 = cat8(*reinterpret_cast<const v4i*>(Ks + KSW8(r32, b0)), *reinterpret_cast<const v4i*>(Ks + KSW8(r32, b0 + 16)));
;     const v8i a1 = cat8(*reinterpret_cast<const v4i*>(Ks + KSW8(32 + r32, b0)), *reinterpret_cast<const v4i*>(Ks + KSW8(32 + r32, b0 + 16)));
;     if (c == 0) { p0 = __builtin_amdgcn_mfma_scale_f32_32x32x64_f8f6f4(a0, qr[c], negm, 0, 0, 0, 0, 0, 0); p1 = __builtin_amdgcn_mfma_scale_f32_32x32x64_f8f6f4(a1, qr[c], negm, 0, 0, 0, 0, 0, 0); }
;     else { p0 = __builtin_amdgcn_mfma_scale_f32_32x32x64_f8f6f4(a0, qr[c], p0, 0, 0, 0, 0, 0, 0); p1 = __builtin_amdgcn_mfma_scale_f32_32x32x64_f8f6f4(a1, qr[c], p1, 0, 0, 0, 0, 0, 0); } }
; }
; __device__ __forceinline__ void pv8(f32x16* o, const char* Vs, v8i pa, int r32, int hi) {
; #pragma unroll
;   for (int d0 = 0; d0 < 4; ++d0) { const int col = 32 * d0 + r32;
;     const v8i b = cat8(*reinterpret_cast<const v4i*>(Vs + VSW8(col, 32 * hi)), *reinterpret_cast<const v4i*>(Vs + VSW8(col, 32 * hi + 16)));
;     o[d0] = __builtin_amdgcn_mfma_scale_f32_32x32x64_f8f6f4(pa, b, o[d0], 0, 0, 0, 0, 0, 0); }
;   const int one4 = 0x38383838;
;   const v8i ones = (v8i){one4, one4, one4, one4, one4, one4, one4, one4};
;   o[4] = __builtin_amdgcn_mfma_scale_f32_32x32x64_f8f6f4(pa, ones, o[4], 0, 0, 0, 0, 0, 0);
; }
.LBB0_68:
	s_add_i32 s39, s39, 2
	s_min_i32 s10, s39, s19
	s_ashr_i32 s11, s10, 31
	s_lshl_b64 s[10:11], s[10:11], 14
	s_add_u32 s10, s4, s10
	s_waitcnt vmcnt(2) lgkmcnt(0)
	s_barrier
	v_add_u32_e32 v114, s34, v219
	ds_read_b128 v[236:239], v114 offset:4096
	v_add_u32_e32 v118, s34, v220
	ds_read_b128 v[240:243], v118 offset:4096
	ds_read_b128 v[114:117], v114
	ds_read_b128 v[118:121], v118
	v_add_u32_e32 v244, s34, v221
	v_add_u32_e32 v248, s34, v222
	s_addc_u32 s11, s5, s11
	s_add_i32 s26, s49, s36
	s_mov_b32 s27, m0
	s_mov_b32 m0, s26
	s_nop 0
	global_load_lds_dwordx4 v199, s[10:11]
	s_mov_b32 m0, s27
	v_exp_f32_e32 v163, v130
	v_exp_f32_e32 v164, v131
	v_exp_f32_e32 v165, v132
	v_exp_f32_e32 v166, v133
	v_exp_f32_e32 v167, v134
	v_exp_f32_e32 v168, v135
	v_exp_f32_e32 v169, v136
	v_exp_f32_e32 v205, v137
	v_exp_f32_e32 v207, v138
	v_exp_f32_e32 v209, v139
	v_exp_f32_e32 v211, v140
	v_exp_f32_e32 v213, v141
	v_exp_f32_e32 v235, v142
	v_exp_f32_e32 v252, v143
	v_exp_f32_e32 v216, v144
	v_exp_f32_e32 v217, v145
	v_exp_f32_e32 v146, v146
	v_exp_f32_e32 v147, v147
	s_waitcnt lgkmcnt(0)
	v_mfma_f32_32x32x64_f8f6f4 v[130:145], v[114:121], v[178:185], v[82:97]
	v_exp_f32_e32 v148, v148
	v_exp_f32_e32 v149, v149
	v_exp_f32_e32 v150, v150
	v_exp_f32_e32 v151, v151
	v_mfma_f32_32x32x64_f8f6f4 v[114:129], v[236:243], v[178:185], v[82:97]
	ds_read_b128 v[236:239], v244 offset:4096
	ds_read_b128 v[240:243], v248 offset:4096
	ds_read_b128 v[244:247], v244
	ds_read_b128 v[248:251], v248
	v_exp_f32_e32 v152, v152
	v_exp_f32_e32 v153, v153
	v_exp_f32_e32 v154, v154
	v_exp_f32_e32 v155, v155
	v_exp_f32_e32 v156, v156
	s_waitcnt lgkmcnt(0)
	v_mfma_f32_32x32x64_f8f6f4 v[130:145], v[244:251], v[170:177], v[130:145]
	v_exp_f32_e32 v157, v157
	v_exp_f32_e32 v158, v158
	v_exp_f32_e32 v159, v159
	v_exp_f32_e32 v160, v160
	v_exp_f32_e32 v161, v161
	v_mfma_f32_32x32x64_f8f6f4 v[114:129], v[236:243], v[170:177], v[114:129]
	s_waitcnt vmcnt(2) lgkmcnt(0)
	s_barrier
	s_add_u32 s10, s6, 0x2000
	s_addc_u32 s11, s7, 0
	s_add_i32 s26, s35, s38
	s_mov_b32 s27, m0
	s_mov_b32 m0, s26
	s_nop 0
	global_load_lds_dwordx4 v1, s[10:11]
	s_mov_b32 m0, s27
	v_add_u32_e32 v244, s50, v223
	v_add_u32_e32 v248, s50, v224
	ds_read_b128 v[244:247], v244 offset:24576
	ds_read_b128 v[248:251], v248 offset:24576
	v_add_u32_e32 v236, s50, v223
	v_add_u32_e32 v240, s50, v224
	ds_read_b128 v[236:239], v236 offset:26624
	ds_read_b128 v[240:243], v240 offset:26624
	v_cvt_pk_fp8_f32 v151, v150, v151
	v_cvt_pk_fp8_f32 v150, v146, v147
	v_cvt_pk_fp8_f32 v151, v152, v153 op_sel:[0,0,1]
	v_cvt_pk_fp8_f32 v150, v148, v149 op_sel:[0,0,1]
	v_cvt_pk_fp8_f32 v152, v154, v155
	v_cvt_pk_fp8_f32 v153, v158, v159
	v_cvt_pk_fp8_f32 v152, v156, v157 op_sel:[0,0,1]
	v_cvt_pk_fp8_f32 v153, v160, v161 op_sel:[0,0,1]
	v_cvt_pk_fp8_f32 v146, v163, v164
	v_cvt_pk_fp8_f32 v147, v167, v168
	v_cvt_pk_fp8_f32 v148, v207, v209
	v_cvt_pk_fp8_f32 v149, v235, v252
	v_cvt_pk_fp8_f32 v146, v165, v166 op_sel:[0,0,1]
	v_cvt_pk_fp8_f32 v147, v169, v205 op_sel:[0,0,1]
	v_cvt_pk_fp8_f32 v148, v211, v213 op_sel:[0,0,1]
	v_cvt_pk_fp8_f32 v149, v216, v217 op_sel:[0,0,1]
	v_add_u32_e32 v156, s50, v223
	v_add_u32_e32 v157, s50, v224
	v_mov_b32_e32 v163, v162
	v_mov_b32_e32 v164, v162
	v_mov_b32_e32 v165, v162
	v_mov_b32_e32 v166, v162
	v_mov_b32_e32 v167, v162
	v_mov_b32_e32 v168, v162
	v_mov_b32_e32 v169, v162
	s_waitcnt lgkmcnt(2)
	v_mfma_f32_32x32x64_f8f6f4 v[2:17], v[146:153], v[244:251], v[2:17]
	ds_read_b128 v[244:247], v156 offset:28672
	ds_read_b128 v[248:251], v157 offset:28672
	v_max3_f32 v154, v130, v131, v132
	v_max3_f32 v155, v133, v134, v135
	v_max3_f32 v154, v154, v136, v137
	v_max3_f32 v155, v155, v138, v139
	v_max3_f32 v154, v154, v140, v141
	s_waitcnt lgkmcnt(2)
	v_mfma_f32_32x32x64_f8f6f4 v[50:65], v[146:153], v[236:243], v[50:65]
	ds_read_b128 v[236:239], v156 offset:30720
	ds_read_b128 v[240:243], v157 offset:30720
	v_max3_f32 v155, v155, v142, v143
	v_max3_f32 v154, v154, v144, v145
	v_max3_f32 v155, v155, v114, v115
	v_max3_f32 v154, v154, v116, v117
	v_max3_f32 v155, v155, v118, v119
	s_waitcnt lgkmcnt(2)
	v_mfma_f32_32x32x64_f8f6f4 v[34:49], v[146:153], v[244:251], v[34:49]
	v_max3_f32 v154, v154, v120, v121
	v_max3_f32 v155, v155, v122, v123
	v_max3_f32 v154, v154, v124, v125
	v_max3_f32 v155, v155, v126, v127
	v_max3_f32 v154, v154, v128, v129
	s_waitcnt lgkmcnt(0)
	v_mfma_f32_32x32x64_f8f6f4 v[18:33], v[146:153], v[236:243], v[18:33]
	v_mfma_f32_32x32x64_f8f6f4 v[66:81], v[146:153], v[162:169], v[66:81]
	v_max_f32_e32 v146, v154, v155
	v_mov_b32_e32 v147, v146
	s_nop 1
	v_permlane32_swap_b32_e32 v146, v147
	v_max_f32_e32 v147, v147, v147
	v_max_f32_e32 v146, v146, v146
	v_max_f32_e32 v146, v146, v147
	v_add_f32_e32 v147, -4.0, v146
	v_cmp_ge_f32_e32 vcc, s82, v147
	s_cmp_eq_u64 vcc, exec
	v_mov_b32_e32 v146, 1.0
	s_cbranch_scc0 .LBB0_76
	v_cmp_gt_f32_e32 vcc, 1.0, v146
	s_cbranch_vccz .LBB0_73

; #define SBAR() __builtin_amdgcn_sched_barrier(0)
; #define WAIT_BAR(N) asm volatile("s_waitcnt vmcnt(" #N ") lgkmcnt(0)\n\ts_barrier" ::: "memory")
; #define RESC(a) do { if (__any((a) < 1.f)) { if (hi == 0) al_l[r32] = (a); asm volatile("s_waitcnt lgkmcnt(0)" ::: "memory"); \
;     for (int d = 0; d < 4; ++d) for (int r = 0; r < 16; ++r) o[d][r] *= al_l[crow(r, hi)]; } } while (0)
; #define ROT() do { const int t_ = s0; s0 = s1; s1 = s2; s2 = t_; } while (0)
; #define WAIT_BAR(N) asm volatile("s_waitcnt vmcnt(" #N ") lgkmcnt(0)\n\ts_barrier" ::: "memory")
; #define RESC(a) do { if (__any((a) < 1.f)) { if (hi == 0) al_l[r32] = (a); asm volatile("s_waitcnt lgkmcnt(0)" ::: "memory"); \
;     for (int d = 0; d < 5; ++d) for (int r = 0; r < 16; ++r) o[d][r] *= al_l[crow(r, hi)]; } } while (0)
; #define ROT() do { const int t_ = s0; s0 = s1; s1 = s2; s2 = t_; } while (0)
; __device__ __forceinline__ void attn_fp8_body(const unsigned char* __restrict__ Q8w, const unsigned char* __restrict__ K8t, const unsigned char* __restrict__ V8t,
;                                               bf16_t* __restrict__ Ob, int seq, char* lds, const int tid) {
;     ...
;     WAIT_BAR(2); ROT();
;   }
;   SBAR(); qkt8(pB0, pB1, KP8(s1), qr, negm, r32, hi);
;   finishSM8(pA0, pA1, pa); SBAR();
;   pv8(o, VP8(s0), pa, r32, hi); partialSM8<false>(pB0, pB1, m_ref, negm, alB);
;   RESC(alB);
.LBB0_73:
	s_add_u32 s6, s6, 0x4000
	s_addc_u32 s7, s7, 0
	s_add_u32 s8, s8, 0x8000
	s_waitcnt vmcnt(2) lgkmcnt(0)
	s_barrier
	s_addc_u32 s9, s9, 0
	s_cmp_ge_i32 s39, s18
	s_cbranch_scc1 .Lattn_exit
	s_mov_b32 s10, s34
	s_mov_b32 s34, s49
	s_branch .LBB0_63
.Lattn_exit:
	v_readlane_b32 s26, v253, 6
	s_nop 3
	s_cmp_lt_u32 s26, 4
	s_cbranch_scc0 .Lattn_exit2
	s_barrier
.Lattn_exit2:
	v_exp_f32_e32 v235, v130
	v_exp_f32_e32 v236, v131
	v_exp_f32_e32 v237, v132
	v_exp_f32_e32 v238, v133
	v_exp_f32_e32 v207, v134
	v_exp_f32_e32 v209, v135
	v_exp_f32_e32 v211, v136
	v_exp_f32_e32 v213, v137
	v_exp_f32_e32 v167, v138
	v_exp_f32_e32 v168, v139
	v_exp_f32_e32 v169, v140
	v_exp_f32_e32 v205, v141
	v_exp_f32_e32 v165, v142
	v_exp_f32_e32 v166, v143
	v_exp_f32_e32 v163, v144
	v_exp_f32_e32 v164, v145
	s_branch .LBB0_78
